# S5 gate epilogue: bias vectors loaded once per unit instead of re-loaded with a full drain after every store
# baseline (speedup 1.0000x reference)
; #define PG8_STAGE(bufoff, gbase, voff) do { _Pragma("unroll") for (int _i = 0; _i < 2; ++_i) \
;         __builtin_amdgcn_global_load_lds((const unsigned*)((const char*)(gbase) + (voff)[_i]), (LAS unsigned*)(lds + (bufoff) + ldsw + _i * 8192), 16, 0, 0); } while (0)
; #define PG8_LDA(dst, b, h) do { _Pragma("unroll") for (int m = 0; m < 4; ++m) _Pragma("unroll") for (int k = 0; k < 2; ++k) dst[m][k] = *(const LAS bf16x8*)(lds + PG8_SA(b, h) + aoff + m * 2048 + k * 1024); } while (0)
; #define PG8_LDB(dst, b, h) do { _Pragma("unroll") for (int n = 0; n < 2; ++n) _Pragma("unroll") for (int k = 0; k < 2; ++k) dst[n][k] = *(const LAS bf16x8*)(lds + PG8_SB(b, h) + boff + n * 2048 + k * 1024); } while (0)
; #define PG8_MMA(ai, bj, At, Bt) do { __builtin_amdgcn_s_setprio(1); _Pragma("unroll") for (int m = 0; m < 4; ++m) _Pragma("unroll") for (int n = 0; n < 2; ++n) _Pragma("unroll") for (int k = 0; k < 2; ++k) \
;         acc[ai][bj][m][n] = __builtin_amdgcn_mfma_f32_16x16x32_bf16(Bt[n][k], At[m][k], acc[ai][bj][m][n], 0, 0, 0); __builtin_amdgcn_s_setprio(0); } while (0)
; #define PG8_WAIT_V(n) asm volatile("s_waitcnt vmcnt(" #n ")" ::: "memory")
; #define PG8_WAIT_L(n) asm volatile("s_waitcnt lgkmcnt(" #n ")" ::: "memory")
; #define PG8_BAR __builtin_amdgcn_s_barrier()
; #define PG8_SCHED __builtin_amdgcn_sched_barrier(0)
; template <class Epi>
; DEVI void gemm_phase(LAS unsigned char* lds, const Gemm g, const Epi& E) {
;     ...
;             PG8_LDB(B0, 0, 0); PG8_SCHED; PG8_LDA(At, 0, 0); PG8_STAGE(PG8_SA(1, 1), a1 + hstepA, voffA);
;             PG8_WAIT_L(8); PG8_BAR; PG8_WAIT_L(0); PG8_MMA(0, 0, At, B0); PG8_BAR; PG8_SCHED;
;             PG8_LDB(B1, 0, 1); PG8_STAGE(PG8_SB(0, 0), b2, voffB);
;             PG8_BAR; PG8_WAIT_L(0); PG8_MMA(0, 1, At, B1); PG8_BAR;
;             PG8_LDA(At, 0, 1); PG8_STAGE(PG8_SA(0, 0), a2, voffA);
;             PG8_BAR; PG8_WAIT_L(0); PG8_MMA(1, 0, At, B0); PG8_BAR; PG8_SCHED;
;             PG8_STAGE(PG8_SB(0, 1), b2 + hstepB, voffB);
;             PG8_WAIT_V(6); PG8_BAR; PG8_MMA(1, 1, At, B1); PG8_BAR;
.LBB0_1346:
	s_add_u32 s14, s12, 0xfffc0080
	s_addc_u32 s15, s13, -1
	s_add_i32 s38, 0, 0x10000
	v_add_u32_e32 v152, s38, v185
	ds_read_b128 v[114:117], v152
	ds_read_b128 v[126:129], v152 offset:1024
	ds_read_b128 v[130:133], v152 offset:2048
	ds_read_b128 v[176:179], v152 offset:3072
	s_cmp_eq_u32 s27, 12
	s_cselect_b32 s17, s1, s15
	s_cselect_b32 s16, s3, s14
	s_cselect_b32 s15, s5, s26
	s_cselect_b32 s14, s18, s19
	v_lshl_add_u64 v[152:153], s[12:13], 0, v[148:149]
	s_add_i32 m0, s11, 0xc000
	ds_read_b128 v[180:183], v187
	ds_read_b128 v[188:191], v187 offset:1024
	ds_read_b128 v[192:195], v187 offset:2048
	ds_read_b128 v[196:199], v187 offset:3072
	ds_read_b128 v[200:203], v187 offset:4096
	ds_read_b128 v[204:207], v187 offset:5120
	ds_read_b128 v[214:217], v187 offset:6144
	ds_read_b128 v[218:221], v187 offset:7168
	global_load_lds_dwordx4 v[152:153], off
	v_lshl_add_u64 v[152:153], s[12:13], 0, v[150:151]
	s_add_i32 m0, s11, 0xe000
	s_nop 0
	global_load_lds_dwordx4 v[152:153], off
	s_waitcnt lgkmcnt(8)
	s_barrier
	s_waitcnt lgkmcnt(0)
	s_setprio 1
	s_waitcnt lgkmcnt(0)
	v_mfma_f32_16x16x32_bf16 v[138:141], v[114:117], v[180:183], v[138:141]
	v_mfma_f32_16x16x32_bf16 v[134:137], v[130:133], v[180:183], v[134:137]
	v_mfma_f32_16x16x32_bf16 v[110:113], v[114:117], v[192:195], v[110:113]
	v_mfma_f32_16x16x32_bf16 v[106:109], v[130:133], v[192:195], v[106:109]
	v_mfma_f32_16x16x32_bf16 v[94:97], v[114:117], v[200:203], v[94:97]
	v_mfma_f32_16x16x32_bf16 v[90:93], v[130:133], v[200:203], v[90:93]
	v_mfma_f32_16x16x32_bf16 v[78:81], v[114:117], v[214:217], v[78:81]
	v_mfma_f32_16x16x32_bf16 v[74:77], v[130:133], v[214:217], v[74:77]
	v_mfma_f32_16x16x32_bf16 v[138:141], v[126:129], v[188:191], v[138:141]
	v_mfma_f32_16x16x32_bf16 v[134:137], v[176:179], v[188:191], v[134:137]
	v_mfma_f32_16x16x32_bf16 v[110:113], v[126:129], v[196:199], v[110:113]
	v_mfma_f32_16x16x32_bf16 v[106:109], v[176:179], v[196:199], v[106:109]
	v_mfma_f32_16x16x32_bf16 v[94:97], v[126:129], v[204:207], v[94:97]
	v_mfma_f32_16x16x32_bf16 v[90:93], v[176:179], v[204:207], v[90:93]
	v_mfma_f32_16x16x32_bf16 v[78:81], v[126:129], v[218:221], v[78:81]
	v_mfma_f32_16x16x32_bf16 v[74:77], v[176:179], v[218:221], v[74:77]
	s_setprio 0
	s_barrier
	s_add_i32 s40, 0, 0x14000
	v_add_u32_e32 v152, s40, v185
	s_add_i32 s38, s38, s47
	ds_read_b128 v[222:225], v152
	ds_read_b128 v[226:229], v152 offset:1024
	ds_read_b128 v[230:233], v152 offset:2048
	ds_read_b128 v[234:237], v152 offset:3072
	v_lshl_add_u64 v[152:153], s[14:15], 0, v[8:9]
	s_mov_b32 m0, s38
	v_lshl_add_u64 v[162:163], s[14:15], 0, v[146:147]
	global_load_lds_dwordx4 v[152:153], off
	s_add_i32 m0, s38, 0x2000
	s_nop 0
	global_load_lds_dwordx4 v[162:163], off
	s_barrier
	s_waitcnt lgkmcnt(0)
	s_setprio 1
	s_waitcnt lgkmcnt(0)
	v_mfma_f32_16x16x32_bf16 v[122:125], v[222:225], v[180:183], v[122:125]
	v_mfma_f32_16x16x32_bf16 v[118:121], v[230:233], v[180:183], v[118:121]
	v_mfma_f32_16x16x32_bf16 v[102:105], v[222:225], v[192:195], v[102:105]
	v_mfma_f32_16x16x32_bf16 v[98:101], v[230:233], v[192:195], v[98:101]
	v_mfma_f32_16x16x32_bf16 v[86:89], v[222:225], v[200:203], v[86:89]
	v_mfma_f32_16x16x32_bf16 v[82:85], v[230:233], v[200:203], v[82:85]
	v_mfma_f32_16x16x32_bf16 v[70:73], v[222:225], v[214:217], v[70:73]
	v_mfma_f32_16x16x32_bf16 v[66:69], v[230:233], v[214:217], v[66:69]
	v_mfma_f32_16x16x32_bf16 v[122:125], v[226:229], v[188:191], v[122:125]
	v_mfma_f32_16x16x32_bf16 v[118:121], v[234:237], v[188:191], v[118:121]
	v_mfma_f32_16x16x32_bf16 v[102:105], v[226:229], v[196:199], v[102:105]
	v_mfma_f32_16x16x32_bf16 v[98:101], v[234:237], v[196:199], v[98:101]
	v_mfma_f32_16x16x32_bf16 v[86:89], v[226:229], v[204:207], v[86:89]
	v_mfma_f32_16x16x32_bf16 v[82:85], v[234:237], v[204:207], v[82:85]
	v_mfma_f32_16x16x32_bf16 v[70:73], v[226:229], v[218:221], v[70:73]
	v_mfma_f32_16x16x32_bf16 v[66:69], v[234:237], v[218:221], v[66:69]
	s_setprio 0
	s_mov_b32 m0, s11
	v_lshl_add_u64 v[164:165], s[16:17], 0, v[142:143]
	s_barrier
	ds_read_b128 v[180:183], v187 offset:16384
	ds_read_b128 v[188:191], v187 offset:17408
	ds_read_b128 v[192:195], v187 offset:18432
	ds_read_b128 v[196:199], v187 offset:19456
	ds_read_b128 v[200:203], v187 offset:20480
	ds_read_b128 v[204:207], v187 offset:21504
	ds_read_b128 v[214:217], v187 offset:22528
	ds_read_b128 v[218:221], v187 offset:23552
	global_load_lds_dwordx4 v[164:165], off
	v_lshl_add_u64 v[208:209], s[16:17], 0, v[144:145]
	s_mov_b32 m0, s66
	s_nop 0
	global_load_lds_dwordx4 v[208:209], off
	s_barrier
	s_waitcnt lgkmcnt(0)
	s_setprio 1
	s_waitcnt lgkmcnt(0)
	v_mfma_f32_16x16x32_bf16 v[62:65], v[114:117], v[180:183], v[62:65]
	v_mfma_f32_16x16x32_bf16 v[58:61], v[130:133], v[180:183], v[58:61]
	v_mfma_f32_16x16x32_bf16 v[46:49], v[114:117], v[192:195], v[46:49]
	v_mfma_f32_16x16x32_bf16 v[42:45], v[130:133], v[192:195], v[42:45]
	v_mfma_f32_16x16x32_bf16 v[30:33], v[114:117], v[200:203], v[30:33]
	v_mfma_f32_16x16x32_bf16 v[26:29], v[130:133], v[200:203], v[26:29]
	v_mfma_f32_16x16x32_bf16 v[14:17], v[114:117], v[214:217], v[14:17]
	v_mfma_f32_16x16x32_bf16 v[10:13], v[130:133], v[214:217], v[10:13]
	v_mfma_f32_16x16x32_bf16 v[62:65], v[126:129], v[188:191], v[62:65]
	v_mfma_f32_16x16x32_bf16 v[58:61], v[176:179], v[188:191], v[58:61]
	v_mfma_f32_16x16x32_bf16 v[46:49], v[126:129], v[196:199], v[46:49]
	v_mfma_f32_16x16x32_bf16 v[42:45], v[176:179], v[196:199], v[42:45]
	v_mfma_f32_16x16x32_bf16 v[30:33], v[126:129], v[204:207], v[30:33]
	v_mfma_f32_16x16x32_bf16 v[26:29], v[176:179], v[204:207], v[26:29]
	v_mfma_f32_16x16x32_bf16 v[14:17], v[126:129], v[218:221], v[14:17]
	v_mfma_f32_16x16x32_bf16 v[10:13], v[176:179], v[218:221], v[10:13]
	s_setprio 0
	s_barrier
; #define PG8_STAGE(bufoff, gbase, voff) do { _Pragma("unroll") for (int _i = 0; _i < 2; ++_i) \
;         __builtin_amdgcn_global_load_lds((const unsigned*)((const char*)(gbase) + (voff)[_i]), (LAS unsigned*)(lds + (bufoff) + ldsw + _i * 8192), 16, 0, 0); } while (0)
; #define PG8_LDA(dst, b, h) do { _Pragma("unroll") for (int m = 0; m < 4; ++m) _Pragma("unroll") for (int k = 0; k < 2; ++k) dst[m][k] = *(const LAS bf16x8*)(lds + PG8_SA(b, h) + aoff + m * 2048 + k * 1024); } while (0)
; #define PG8_LDB(dst, b, h) do { _Pragma("unroll") for (int n = 0; n < 2; ++n) _Pragma("unroll") for (int k = 0; k < 2; ++k) dst[n][k] = *(const LAS bf16x8*)(lds + PG8_SB(b, h) + boff + n * 2048 + k * 1024); } while (0)
; #define PG8_MMA(ai, bj, At, Bt) do { __builtin_amdgcn_s_setprio(1); _Pragma("unroll") for (int m = 0; m < 4; ++m) _Pragma("unroll") for (int n = 0; n < 2; ++n) _Pragma("unroll") for (int k = 0; k < 2; ++k) \
;         acc[ai][bj][m][n] = __builtin_amdgcn_mfma_f32_16x16x32_bf16(Bt[n][k], At[m][k], acc[ai][bj][m][n], 0, 0, 0); __builtin_amdgcn_s_setprio(0); } while (0)
; #define PG8_WAIT_V(n) asm volatile("s_waitcnt vmcnt(" #n ")" ::: "memory")
; #define PG8_WAIT_L(n) asm volatile("s_waitcnt lgkmcnt(" #n ")" ::: "memory")
; #define PG8_BAR __builtin_amdgcn_s_barrier()
; #define PG8_SCHED __builtin_amdgcn_sched_barrier(0)
; template <class Epi>
; DEVI void gemm_phase(LAS unsigned char* lds, const Gemm g, const Epi& E) {
;     ...
;             PG8_STAGE(PG8_SB(0, 1), b2 + hstepB, voffB);
;             PG8_WAIT_V(6); PG8_BAR; PG8_MMA(1, 1, At, B1); PG8_BAR;
;             PG8_LDB(B0, 1, 0); PG8_SCHED; PG8_LDA(At, 1, 0); PG8_STAGE(PG8_SA(0, 1), a2 + hstepA, voffA);
;             PG8_WAIT_L(8); PG8_BAR; PG8_WAIT_L(0); PG8_MMA(0, 0, At, B0); PG8_BAR; PG8_SCHED;
;             PG8_LDB(B1, 1, 1); PG8_STAGE(PG8_SB(1, 0), b3, voffB);
;             PG8_BAR; PG8_WAIT_L(0); PG8_MMA(0, 1, At, B1); PG8_BAR;
;             PG8_LDA(At, 1, 1); PG8_STAGE(PG8_SA(1, 0), a3, voffA);
	s_add_u32 s38, s14, 0x40000
	s_addc_u32 s39, s15, 0
	s_add_i32 s40, s40, s47
	v_lshl_add_u64 v[114:115], s[38:39], 0, v[8:9]
	s_mov_b32 m0, s40
	s_nop 0
	global_load_lds_dwordx4 v[114:115], off
	v_lshl_add_u64 v[114:115], s[38:39], 0, v[146:147]
	s_add_i32 m0, s40, 0x2000
	s_nop 0
	global_load_lds_dwordx4 v[114:115], off
	s_waitcnt vmcnt(6)
	s_barrier
	s_setprio 1
	v_mfma_f32_16x16x32_bf16 v[54:57], v[222:225], v[180:183], v[54:57]
	v_mfma_f32_16x16x32_bf16 v[50:53], v[230:233], v[180:183], v[50:53]
	v_mfma_f32_16x16x32_bf16 v[38:41], v[222:225], v[192:195], v[38:41]
	v_mfma_f32_16x16x32_bf16 v[34:37], v[230:233], v[192:195], v[34:37]
	v_mfma_f32_16x16x32_bf16 v[22:25], v[222:225], v[200:203], v[22:25]
	v_mfma_f32_16x16x32_bf16 v[18:21], v[230:233], v[200:203], v[18:21]
	v_mfma_f32_16x16x32_bf16 v[4:7], v[222:225], v[214:217], v[4:7]
	v_mfma_f32_16x16x32_bf16 v[0:3], v[230:233], v[214:217], v[0:3]
	v_mfma_f32_16x16x32_bf16 v[54:57], v[226:229], v[188:191], v[54:57]
	v_mfma_f32_16x16x32_bf16 v[50:53], v[234:237], v[188:191], v[50:53]
	v_mfma_f32_16x16x32_bf16 v[38:41], v[226:229], v[196:199], v[38:41]
	v_mfma_f32_16x16x32_bf16 v[34:37], v[234:237], v[196:199], v[34:37]
	v_mfma_f32_16x16x32_bf16 v[22:25], v[226:229], v[204:207], v[22:25]
	v_mfma_f32_16x16x32_bf16 v[18:21], v[234:237], v[204:207], v[18:21]
	v_mfma_f32_16x16x32_bf16 v[4:7], v[226:229], v[218:221], v[4:7]
	v_mfma_f32_16x16x32_bf16 v[0:3], v[234:237], v[218:221], v[0:3]
	s_setprio 0
	s_add_i32 s38, 0, 0x18000
	v_add_u32_e32 v176, s38, v185
	s_barrier
	ds_read_b128 v[114:117], v176
	ds_read_b128 v[126:129], v176 offset:1024
	ds_read_b128 v[130:133], v176 offset:2048
	ds_read_b128 v[176:179], v176 offset:3072
	s_add_u32 s16, s16, 0x40000
	s_addc_u32 s17, s17, 0
	s_mov_b32 m0, s68
	v_lshl_add_u64 v[222:223], s[16:17], 0, v[142:143]
	ds_read_b128 v[180:183], v187 offset:32768
	ds_read_b128 v[188:191], v187 offset:33792
	ds_read_b128 v[192:195], v187 offset:34816
	ds_read_b128 v[196:199], v187 offset:35840
	ds_read_b128 v[200:203], v187 offset:36864
	ds_read_b128 v[204:207], v187 offset:37888
	ds_read_b128 v[214:217], v187 offset:38912
	ds_read_b128 v[218:221], v187 offset:39936
	global_load_lds_dwordx4 v[222:223], off
	v_lshl_add_u64 v[222:223], s[16:17], 0, v[144:145]
	s_mov_b32 m0, s69
	s_nop 0
	global_load_lds_dwordx4 v[222:223], off
	s_waitcnt lgkmcnt(8)
	s_barrier
	s_waitcnt lgkmcnt(0)
	s_setprio 1
	s_waitcnt lgkmcnt(0)
	v_mfma_f32_16x16x32_bf16 v[138:141], v[114:117], v[180:183], v[138:141]
	v_mfma_f32_16x16x32_bf16 v[134:137], v[130:133], v[180:183], v[134:137]
	v_mfma_f32_16x16x32_bf16 v[110:113], v[114:117], v[192:195], v[110:113]
	v_mfma_f32_16x16x32_bf16 v[106:109], v[130:133], v[192:195], v[106:109]
	v_mfma_f32_16x16x32_bf16 v[94:97], v[114:117], v[200:203], v[94:97]
	v_mfma_f32_16x16x32_bf16 v[90:93], v[130:133], v[200:203], v[90:93]
	v_mfma_f32_16x16x32_bf16 v[78:81], v[114:117], v[214:217], v[78:81]
	v_mfma_f32_16x16x32_bf16 v[74:77], v[130:133], v[214:217], v[74:77]
	v_mfma_f32_16x16x32_bf16 v[138:141], v[126:129], v[188:191], v[138:141]
	v_mfma_f32_16x16x32_bf16 v[134:137], v[176:179], v[188:191], v[134:137]
	v_mfma_f32_16x16x32_bf16 v[110:113], v[126:129], v[196:199], v[110:113]
	v_mfma_f32_16x16x32_bf16 v[106:109], v[176:179], v[196:199], v[106:109]
	v_mfma_f32_16x16x32_bf16 v[94:97], v[126:129], v[204:207], v[94:97]
	v_mfma_f32_16x16x32_bf16 v[90:93], v[176:179], v[204:207], v[90:93]
	v_mfma_f32_16x16x32_bf16 v[78:81], v[126:129], v[218:221], v[78:81]
	v_mfma_f32_16x16x32_bf16 v[74:77], v[176:179], v[218:221], v[74:77]
	s_setprio 0
	s_barrier
	s_add_i32 s16, 0, 0x1c000
	s_add_i32 s17, s38, s47
	v_add_u32_e32 v213, s16, v185
	v_lshl_add_u64 v[152:153], v[152:153], 0, s[70:71]
	s_mov_b32 m0, s17
	ds_read_b128 v[222:225], v213
	ds_read_b128 v[226:229], v213 offset:1024
	ds_read_b128 v[230:233], v213 offset:2048
	ds_read_b128 v[234:237], v213 offset:3072
	global_load_lds_dwordx4 v[152:153], off
	v_lshl_add_u64 v[152:153], v[162:163], 0, s[70:71]
	s_add_i32 m0, s17, 0x2000
	s_nop 0
	global_load_lds_dwordx4 v[152:153], off
	s_barrier
	s_waitcnt lgkmcnt(0)
	s_setprio 1
	s_waitcnt lgkmcnt(0)
	v_mfma_f32_16x16x32_bf16 v[122:125], v[222:225], v[180:183], v[122:125]
	v_mfma_f32_16x16x32_bf16 v[118:121], v[230:233], v[180:183], v[118:121]
	v_mfma_f32_16x16x32_bf16 v[102:105], v[222:225], v[192:195], v[102:105]
	v_mfma_f32_16x16x32_bf16 v[98:101], v[230:233], v[192:195], v[98:101]
	v_mfma_f32_16x16x32_bf16 v[86:89], v[222:225], v[200:203], v[86:89]
	v_mfma_f32_16x16x32_bf16 v[82:85], v[230:233], v[200:203], v[82:85]
	v_mfma_f32_16x16x32_bf16 v[70:73], v[222:225], v[214:217], v[70:73]
	v_mfma_f32_16x16x32_bf16 v[66:69], v[230:233], v[214:217], v[66:69]
	v_mfma_f32_16x16x32_bf16 v[122:125], v[226:229], v[188:191], v[122:125]
	v_mfma_f32_16x16x32_bf16 v[118:121], v[234:237], v[188:191], v[118:121]
	v_mfma_f32_16x16x32_bf16 v[102:105], v[226:229], v[196:199], v[102:105]
	v_mfma_f32_16x16x32_bf16 v[98:101], v[234:237], v[196:199], v[98:101]
	v_mfma_f32_16x16x32_bf16 v[86:89], v[226:229], v[204:207], v[86:89]
	v_mfma_f32_16x16x32_bf16 v[82:85], v[234:237], v[204:207], v[82:85]
	v_mfma_f32_16x16x32_bf16 v[70:73], v[226:229], v[218:221], v[70:73]
	v_mfma_f32_16x16x32_bf16 v[66:69], v[234:237], v[218:221], v[66:69]
	s_setprio 0
	s_mov_b32 m0, s80
	v_lshl_add_u64 v[152:153], v[164:165], 0, s[70:71]
	s_barrier
	ds_read_b128 v[180:183], v187 offset:49152
	ds_read_b128 v[188:191], v187 offset:50176
	ds_read_b128 v[192:195], v187 offset:51200
	ds_read_b128 v[196:199], v187 offset:52224
	ds_read_b128 v[200:203], v187 offset:53248
	ds_read_b128 v[204:207], v187 offset:54272
	ds_read_b128 v[214:217], v187 offset:55296
	ds_read_b128 v[218:221], v187 offset:56320
	global_load_lds_dwordx4 v[152:153], off
	v_lshl_add_u64 v[152:153], v[208:209], 0, s[70:71]
	s_mov_b32 m0, s81
	s_nop 0
	global_load_lds_dwordx4 v[152:153], off
	s_barrier
; #define PG8_STAGE(bufoff, gbase, voff) do { _Pragma("unroll") for (int _i = 0; _i < 2; ++_i) \
;         __builtin_amdgcn_global_load_lds((const unsigned*)((const char*)(gbase) + (voff)[_i]), (LAS unsigned*)(lds + (bufoff) + ldsw + _i * 8192), 16, 0, 0); } while (0)
; #define PG8_MMA(ai, bj, At, Bt) do { __builtin_amdgcn_s_setprio(1); _Pragma("unroll") for (int m = 0; m < 4; ++m) _Pragma("unroll") for (int n = 0; n < 2; ++n) _Pragma("unroll") for (int k = 0; k < 2; ++k) \
;         acc[ai][bj][m][n] = __builtin_amdgcn_mfma_f32_16x16x32_bf16(Bt[n][k], At[m][k], acc[ai][bj][m][n], 0, 0, 0); __builtin_amdgcn_s_setprio(0); } while (0)
; #define PG8_WAIT_V(n) asm volatile("s_waitcnt vmcnt(" #n ")" ::: "memory")
; #define PG8_WAIT_L(n) asm volatile("s_waitcnt lgkmcnt(" #n ")" ::: "memory")
; template <class Epi>
; DEVI void gemm_phase(LAS unsigned char* lds, const Gemm g, const Epi& E) {
;     ...
;             PG8_BAR; PG8_WAIT_L(0); PG8_MMA(1, 0, At, B0); PG8_BAR; PG8_SCHED;
;             PG8_STAGE(PG8_SB(1, 1), b3 + hstepB, voffB);
;             PG8_WAIT_V(6); PG8_BAR; PG8_MMA(1, 1, At, B1); PG8_BAR;
;         }
;     ...
;                 if constexpr (Epi::PRE) {
; #pragma unroll
;                     for (int m = 0; m < 2; ++m)
; #pragma unroll
;                         for (int bj = 0; bj < 2; ++bj)
; #pragma unroll
;                             for (int n = 0; n < 2; ++n) pre[m][bj][n] = E.load(row0 + ai * HALF + (m0 + m) * 16, col0 + bj * HALF + n * NST);
;                 }
; #pragma unroll
;                 for (int mm = 0; mm < 2; ++mm) {
;                     const int m = m0 + mm;
;                     const int r = row0 + ai * HALF + m * 16; float rs = 1.f, part = 0.f;
;                     if constexpr (Epi::RS) rs = rsv[ai * 4 + m];
;                     if constexpr (Epi::PAIR) E.pair8(cur.b, r, cur.pn * HALF + wc * 32 + 8 * fq, acc[ai][0][m][0] * rs, acc[ai][0][m][1] * rs, acc[ai][1][m][0] * rs, acc[ai][1][m][1] * rs);
;                     else
; #pragma unroll
;                     for (int bj = 0; bj < 2; ++bj) {
;                         const int c = col0 + bj * HALF; f32x4 v0 = acc[ai][bj][m][0], v1 = acc[ai][bj][m][1];
;                         if constexpr (Epi::RS) { v0 = v0 * rs; v1 = v1 * rs; }
;                         if constexpr (Epi::PRE) part += E.frag_pre8(cur.b, r, c, v0, v1, pre[mm][bj][0], pre[mm][bj][1]);
	s_waitcnt lgkmcnt(0)
	s_setprio 1
	s_waitcnt lgkmcnt(0)
	v_mfma_f32_16x16x32_bf16 v[62:65], v[114:117], v[180:183], v[62:65]
	v_mfma_f32_16x16x32_bf16 v[58:61], v[130:133], v[180:183], v[58:61]
	v_mfma_f32_16x16x32_bf16 v[46:49], v[114:117], v[192:195], v[46:49]
	v_mfma_f32_16x16x32_bf16 v[42:45], v[130:133], v[192:195], v[42:45]
	v_mfma_f32_16x16x32_bf16 v[30:33], v[114:117], v[200:203], v[30:33]
	v_mfma_f32_16x16x32_bf16 v[26:29], v[130:133], v[200:203], v[26:29]
	v_mfma_f32_16x16x32_bf16 v[14:17], v[114:117], v[214:217], v[14:17]
	v_mfma_f32_16x16x32_bf16 v[10:13], v[130:133], v[214:217], v[10:13]
	v_mfma_f32_16x16x32_bf16 v[62:65], v[126:129], v[188:191], v[62:65]
	v_mfma_f32_16x16x32_bf16 v[58:61], v[176:179], v[188:191], v[58:61]
	v_mfma_f32_16x16x32_bf16 v[46:49], v[126:129], v[196:199], v[46:49]
	v_mfma_f32_16x16x32_bf16 v[42:45], v[176:179], v[196:199], v[42:45]
	v_mfma_f32_16x16x32_bf16 v[30:33], v[126:129], v[204:207], v[30:33]
	v_mfma_f32_16x16x32_bf16 v[26:29], v[176:179], v[204:207], v[26:29]
	v_mfma_f32_16x16x32_bf16 v[14:17], v[126:129], v[218:221], v[14:17]
	v_mfma_f32_16x16x32_bf16 v[10:13], v[176:179], v[218:221], v[10:13]
	s_setprio 0
	s_barrier
	s_add_u32 s14, s14, 0x40080
	s_addc_u32 s15, s15, 0
	s_add_i32 s16, s16, s47
	v_lshl_add_u64 v[114:115], s[14:15], 0, v[8:9]
	s_mov_b32 m0, s16
	s_nop 0
	global_load_lds_dwordx4 v[114:115], off
	v_lshl_add_u64 v[114:115], s[14:15], 0, v[146:147]
	s_add_i32 m0, s16, 0x2000
	s_nop 0
	global_load_lds_dwordx4 v[114:115], off
	s_waitcnt vmcnt(6)
	s_barrier
	s_setprio 1
	v_mfma_f32_16x16x32_bf16 v[54:57], v[222:225], v[180:183], v[54:57]
	v_mfma_f32_16x16x32_bf16 v[50:53], v[230:233], v[180:183], v[50:53]
	v_mfma_f32_16x16x32_bf16 v[38:41], v[222:225], v[192:195], v[38:41]
	v_mfma_f32_16x16x32_bf16 v[34:37], v[230:233], v[192:195], v[34:37]
	v_mfma_f32_16x16x32_bf16 v[22:25], v[222:225], v[200:203], v[22:25]
	v_mfma_f32_16x16x32_bf16 v[18:21], v[230:233], v[200:203], v[18:21]
	v_mfma_f32_16x16x32_bf16 v[4:7], v[222:225], v[214:217], v[4:7]
	v_mfma_f32_16x16x32_bf16 v[0:3], v[230:233], v[214:217], v[0:3]
	v_mfma_f32_16x16x32_bf16 v[54:57], v[226:229], v[188:191], v[54:57]
	v_mfma_f32_16x16x32_bf16 v[50:53], v[234:237], v[188:191], v[50:53]
	v_mfma_f32_16x16x32_bf16 v[38:41], v[226:229], v[196:199], v[38:41]
	v_mfma_f32_16x16x32_bf16 v[34:37], v[234:237], v[196:199], v[34:37]
	v_mfma_f32_16x16x32_bf16 v[22:25], v[226:229], v[204:207], v[22:25]
	v_mfma_f32_16x16x32_bf16 v[18:21], v[234:237], v[204:207], v[18:21]
	v_mfma_f32_16x16x32_bf16 v[4:7], v[226:229], v[218:221], v[4:7]
	v_mfma_f32_16x16x32_bf16 v[0:3], v[234:237], v[218:221], v[0:3]
	s_setprio 0
	s_add_i32 s27, s27, 2
	s_add_u32 s12, s12, 0x100
	s_addc_u32 s13, s13, 0
	s_add_u32 s19, s19, 0x100
	s_addc_u32 s26, s26, 0
	s_cmp_gt_u32 s27, 13
	s_barrier
	s_cbranch_scc0 .LBB0_1346
	v_lshl_add_u32 v180, s10, 8, v184
	v_lshl_or_b32 v152, s0, 8, v186
	v_ashrrev_i32_e32 v181, 31, v180
	v_lshlrev_b64 v[178:179], 11, v[180:181]
	v_ashrrev_i32_e32 v153, 31, v152
	v_lshl_add_u64 v[114:115], s[24:25], 0, v[178:179]
	v_lshlrev_b64 v[176:177], 1, v[152:153]
	v_lshl_add_u64 v[114:115], v[114:115], 0, v[176:177]
	global_load_dwordx4 v[188:191], v[114:115], off
	global_load_dwordx4 v[130:133], v[114:115], off offset:256
	v_or_b32_e32 v114, 16, v180
	v_ashrrev_i32_e32 v115, 31, v114
	v_lshlrev_b64 v[182:183], 11, v[114:115]
	v_readlane_b32 s48, v251, 40
	v_lshl_add_u64 v[114:115], s[24:25], 0, v[182:183]
	v_readlane_b32 s54, v251, 46
	v_readlane_b32 s55, v251, 47
	v_lshl_add_u64 v[114:115], v[114:115], 0, v[176:177]
	global_load_dwordx4 v[126:129], v[114:115], off
	s_nop 0
	global_load_dwordx4 v[114:117], v[114:115], off offset:256
	v_lshl_add_u64 v[152:153], v[152:153], 2, s[54:55]
	global_load_dwordx4 v[214:217], v[152:153], off
	global_load_dwordx4 v[218:221], v[152:153], off offset:16
	global_load_dwordx4 v[222:225], v[152:153], off offset:512
	global_load_dwordx4 v[226:229], v[152:153], off offset:528
	s_mov_b64 s[0:1], 0x40000
	v_readlane_b32 s52, v251, 44
	v_readlane_b32 s56, v251, 48
	v_readlane_b32 s57, v251, 49
	v_readlane_b32 s58, v251, 50
	v_readlane_b32 s59, v251, 51
	v_readlane_b32 s60, v251, 52
	v_readlane_b32 s61, v251, 53
	v_readlane_b32 s62, v251, 54
	v_readlane_b32 s63, v251, 55
	s_and_b64 vcc, exec, s[36:37]
	s_mov_b32 s10, s2
	s_mov_b64 s[14:15], s[8:9]
	s_mov_b64 s[12:13], s[6:7]
	s_mov_b64 s[56:57], s[42:43]
	s_mov_b64 s[58:59], s[44:45]
	s_mov_b32 s60, s41
	s_mov_b32 s61, s83
	s_mov_b32 s62, s84
	s_mov_b32 s63, s85
	v_readlane_b32 s55, v254, 0
	s_movk_i32 s52, 0x110
	v_readlane_b32 s49, v251, 41
	v_readlane_b32 s50, v251, 42
	v_readlane_b32 s51, v251, 43
	v_readlane_b32 s53, v251, 45
	v_readlane_b32 s40, v254, 1
	s_waitcnt vmcnt(0)
; template <class Epi>
; DEVI void gemm_phase(LAS unsigned char* lds, const Gemm g, const Epi& E) {
;     ...
; #pragma unroll
;                 for (int mm = 0; mm < 2; ++mm) {
;                     const int m = m0 + mm;
;                     const int r = row0 + ai * HALF + m * 16; float rs = 1.f, part = 0.f;
;                     if constexpr (Epi::RS) rs = rsv[ai * 4 + m];
;                     if constexpr (Epi::PAIR) E.pair8(cur.b, r, cur.pn * HALF + wc * 32 + 8 * fq, acc[ai][0][m][0] * rs, acc[ai][0][m][1] * rs, acc[ai][1][m][0] * rs, acc[ai][1][m][1] * rs);
;                     else
; #pragma unroll
;                     for (int bj = 0; bj < 2; ++bj) {
;                         const int c = col0 + bj * HALF; f32x4 v0 = acc[ai][bj][m][0], v1 = acc[ai][bj][m][1];
;                         if constexpr (Epi::RS) { v0 = v0 * rs; v1 = v1 * rs; }
;                         if constexpr (Epi::PRE) part += E.frag_pre8(cur.b, r, c, v0, v1, pre[mm][bj][0], pre[mm][bj][1]);
;                         else if constexpr (Epi::PERM) E.frag8(cur.b, r, c, v0, v1);
;                         else { E.frag(cur.b, r, c, v0); E.frag(cur.b, r, c + 16, v1); }
	v_and_b32_e32 v163, 0xffff0000, v188
	v_lshlrev_b32_e32 v162, 16, v188
	v_add_f32_e32 v134, v134, v218
	v_add_f32_e32 v138, v138, v214
	v_add_f32_e32 v139, v139, v215
	v_mul_f32_e32 v138, 0xbfb8aa3b, v138
	v_mul_f32_e32 v139, 0xbfb8aa3b, v139
	v_add_f32_e32 v135, v135, v219
	v_exp_f32_e32 v138, v138
	v_mul_f32_e32 v134, 0xbfb8aa3b, v134
	v_exp_f32_e32 v139, v139
	v_mul_f32_e32 v135, 0xbfb8aa3b, v135
	v_exp_f32_e32 v134, v134
	v_exp_f32_e32 v135, v135
	v_add_f32_e32 v138, 1.0, v138
	v_add_f32_e32 v139, 1.0, v139
	v_rcp_f32_e32 v138, v138
	v_add_f32_e32 v134, 1.0, v134
	v_rcp_f32_e32 v139, v139
	v_add_f32_e32 v135, 1.0, v135
	v_rcp_f32_e32 v134, v134
	v_rcp_f32_e32 v135, v135
	v_pk_mul_f32 v[138:139], v[138:139], v[162:163]
	v_and_b32_e32 v163, 0xffff0000, v190
	v_lshlrev_b32_e32 v162, 16, v190
	v_pk_mul_f32 v[162:163], v[134:135], v[162:163]
	v_add_f32_e32 v135, v136, v220
	v_mul_f32_e32 v135, 0xbfb8aa3b, v135
	v_exp_f32_e32 v135, v135
	v_add_f32_e32 v134, v140, v216
	v_mul_f32_e32 v134, 0xbfb8aa3b, v134
	v_exp_f32_e32 v134, v134
	v_add_f32_e32 v135, 1.0, v135
	v_rcp_f32_e32 v136, v135
	v_add_f32_e32 v135, v141, v217
	v_mul_f32_e32 v135, 0xbfb8aa3b, v135
	v_exp_f32_e32 v135, v135
	v_add_f32_e32 v134, 1.0, v134
	v_rcp_f32_e32 v134, v134
	v_and_b32_e32 v141, 0xffff0000, v189
	v_add_f32_e32 v135, 1.0, v135
	v_rcp_f32_e32 v135, v135
	v_lshlrev_b32_e32 v140, 16, v189
	v_pk_mul_f32 v[140:141], v[134:135], v[140:141]
	v_add_f32_e32 v134, v137, v221
	v_mul_f32_e32 v134, 0xbfb8aa3b, v134
	v_exp_f32_e32 v134, v134
	v_and_b32_e32 v135, 0xffff0000, v191
	v_add_f32_e32 v134, 1.0, v134
	v_rcp_f32_e32 v137, v134
	v_lshlrev_b32_e32 v134, 16, v191
	v_pk_mul_f32 v[164:165], v[136:137], v[134:135]
	v_cvt_pk_bf16_f32 v134, v138, v139
	v_lshl_add_u64 v[138:139], s[64:65], 0, v[178:179]
	v_cvt_pk_bf16_f32 v135, v140, v141
	v_cvt_pk_bf16_f32 v136, v162, v163
	v_cvt_pk_bf16_f32 v137, v164, v165
	v_lshl_add_u64 v[138:139], v[138:139], 0, v[176:177]
	global_store_dwordx4 v[138:139], v[134:137], off
	s_nop 0
	v_and_b32_e32 v141, 0xffff0000, v130
	v_lshlrev_b32_e32 v140, 16, v130
	v_lshlrev_b32_e32 v130, 16, v133
	v_add_f32_e32 v118, v118, v226
	v_add_f32_e32 v119, v119, v227
	v_add_f32_e32 v122, v122, v222
	v_mul_f32_e32 v118, 0xbfb8aa3b, v118
	v_add_f32_e32 v123, v123, v223
	v_mul_f32_e32 v119, 0xbfb8aa3b, v119
	v_add_f32_e32 v124, v124, v224
	v_add_f32_e32 v120, v120, v228
	v_add_f32_e32 v125, v125, v225
	v_add_f32_e32 v121, v121, v229
	v_mul_f32_e32 v122, 0xbfb8aa3b, v122
	v_exp_f32_e32 v118, v118
	v_mul_f32_e32 v123, 0xbfb8aa3b, v123
	v_exp_f32_e32 v119, v119
	v_mul_f32_e32 v124, 0xbfb8aa3b, v124
	v_mul_f32_e32 v120, 0xbfb8aa3b, v120
	v_mul_f32_e32 v125, 0xbfb8aa3b, v125
	v_mul_f32_e32 v121, 0xbfb8aa3b, v121
	v_exp_f32_e32 v122, v122
	v_exp_f32_e32 v123, v123
	v_exp_f32_e32 v124, v124
	v_exp_f32_e32 v120, v120
	v_exp_f32_e32 v125, v125
	v_exp_f32_e32 v121, v121
	v_add_f32_e32 v118, 1.0, v118
	v_add_f32_e32 v119, 1.0, v119
	v_add_f32_e32 v122, 1.0, v122
	v_rcp_f32_e32 v118, v118
	v_add_f32_e32 v123, 1.0, v123
	v_rcp_f32_e32 v119, v119
	v_add_f32_e32 v124, 1.0, v124
	v_add_f32_e32 v120, 1.0, v120
	v_add_f32_e32 v125, 1.0, v125
	v_add_f32_e32 v121, 1.0, v121
	v_rcp_f32_e32 v122, v122
	v_rcp_f32_e32 v123, v123
	v_rcp_f32_e32 v124, v124
	v_rcp_f32_e32 v120, v120
	v_rcp_f32_e32 v125, v125
	v_rcp_f32_e32 v121, v121
	v_and_b32_e32 v135, 0xffff0000, v132
	v_lshlrev_b32_e32 v134, 16, v132
	v_pk_mul_f32 v[118:119], v[118:119], v[134:135]
	v_and_b32_e32 v135, 0xffff0000, v131
	v_lshlrev_b32_e32 v134, 16, v131
	v_and_b32_e32 v131, 0xffff0000, v133
	v_pk_mul_f32 v[122:123], v[122:123], v[140:141]
	v_pk_mul_f32 v[124:125], v[124:125], v[134:135]
	v_pk_mul_f32 v[130:131], v[120:121], v[130:131]
	v_cvt_pk_bf16_f32 v120, v122, v123
	v_cvt_pk_bf16_f32 v121, v124, v125
	v_cvt_pk_bf16_f32 v122, v118, v119
	v_cvt_pk_bf16_f32 v123, v130, v131
	global_store_dwordx4 v[138:139], v[120:123], off offset:256
	s_nop 0
	v_add_f32_e32 v106, v106, v218
	v_add_f32_e32 v107, v107, v219
	v_mul_f32_e32 v106, 0xbfb8aa3b, v106
	v_mul_f32_e32 v107, 0xbfb8aa3b, v107
	v_exp_f32_e32 v106, v106
	v_exp_f32_e32 v107, v107
	v_and_b32_e32 v119, 0xffff0000, v128
	v_lshlrev_b32_e32 v118, 16, v128
	v_add_f32_e32 v106, 1.0, v106
	v_add_f32_e32 v107, 1.0, v107
	v_rcp_f32_e32 v106, v106
	v_rcp_f32_e32 v107, v107
	v_add_f32_e32 v110, v110, v214
	v_add_f32_e32 v111, v111, v215
	v_mul_f32_e32 v110, 0xbfb8aa3b, v110
	v_pk_mul_f32 v[118:119], v[106:107], v[118:119]
	v_add_f32_e32 v107, v108, v220
	v_mul_f32_e32 v107, 0xbfb8aa3b, v107
	v_exp_f32_e32 v107, v107
	v_add_f32_e32 v106, v112, v216
	v_mul_f32_e32 v106, 0xbfb8aa3b, v106
	v_exp_f32_e32 v106, v106
	v_add_f32_e32 v107, 1.0, v107
	v_rcp_f32_e32 v108, v107
	v_add_f32_e32 v107, v113, v217
	v_mul_f32_e32 v107, 0xbfb8aa3b, v107
	v_exp_f32_e32 v107, v107
	v_add_f32_e32 v106, 1.0, v106
	v_rcp_f32_e32 v106, v106
	v_and_b32_e32 v113, 0xffff0000, v127
	v_add_f32_e32 v107, 1.0, v107
	v_rcp_f32_e32 v107, v107
	v_lshlrev_b32_e32 v112, 16, v127
	v_mul_f32_e32 v111, 0xbfb8aa3b, v111
	v_exp_f32_e32 v110, v110
	v_pk_mul_f32 v[112:113], v[106:107], v[112:113]
	v_add_f32_e32 v106, v109, v221
	v_exp_f32_e32 v111, v111
	v_mul_f32_e32 v106, 0xbfb8aa3b, v106
	v_exp_f32_e32 v106, v106
	v_add_f32_e32 v110, 1.0, v110
	v_add_f32_e32 v111, 1.0, v111
	v_rcp_f32_e32 v110, v110
	v_rcp_f32_e32 v111, v111
	v_add_f32_e32 v106, 1.0, v106
	v_rcp_f32_e32 v109, v106
	v_and_b32_e32 v123, 0xffff0000, v126
	v_lshlrev_b32_e32 v122, 16, v126
	v_pk_mul_f32 v[110:111], v[110:111], v[122:123]
	v_and_b32_e32 v107, 0xffff0000, v129
	v_lshlrev_b32_e32 v106, 16, v129
	v_pk_mul_f32 v[120:121], v[108:109], v[106:107]
; template <class Epi>
; DEVI void gemm_phase(LAS unsigned char* lds, const Gemm g, const Epi& E) {
;     ...
; #pragma unroll
;                 for (int mm = 0; mm < 2; ++mm) {
;                     const int m = m0 + mm;
;                     const int r = row0 + ai * HALF + m * 16; float rs = 1.f, part = 0.f;
;                     if constexpr (Epi::RS) rs = rsv[ai * 4 + m];
;                     if constexpr (Epi::PAIR) E.pair8(cur.b, r, cur.pn * HALF + wc * 32 + 8 * fq, acc[ai][0][m][0] * rs, acc[ai][0][m][1] * rs, acc[ai][1][m][0] * rs, acc[ai][1][m][1] * rs);
;                     else
; #pragma unroll
;                     for (int bj = 0; bj < 2; ++bj) {
;                         const int c = col0 + bj * HALF; f32x4 v0 = acc[ai][bj][m][0], v1 = acc[ai][bj][m][1];
;                         if constexpr (Epi::RS) { v0 = v0 * rs; v1 = v1 * rs; }
;                         if constexpr (Epi::PRE) part += E.frag_pre8(cur.b, r, c, v0, v1, pre[mm][bj][0], pre[mm][bj][1]);
;                         else if constexpr (Epi::PERM) E.frag8(cur.b, r, c, v0, v1);
;                         else { E.frag(cur.b, r, c, v0); E.frag(cur.b, r, c + 16, v1); }
	v_cvt_pk_bf16_f32 v106, v110, v111
	v_lshl_add_u64 v[110:111], s[64:65], 0, v[182:183]
	v_cvt_pk_bf16_f32 v107, v112, v113
	v_cvt_pk_bf16_f32 v108, v118, v119
	v_cvt_pk_bf16_f32 v109, v120, v121
	v_lshl_add_u64 v[110:111], v[110:111], 0, v[176:177]
	global_store_dwordx4 v[110:111], v[106:109], off
	s_nop 0
	v_and_b32_e32 v113, 0xffff0000, v114
	v_lshlrev_b32_e32 v112, 16, v114
	v_add_f32_e32 v98, v98, v226
	v_add_f32_e32 v99, v99, v227
	v_mul_f32_e32 v98, 0xbfb8aa3b, v98
	v_mul_f32_e32 v99, 0xbfb8aa3b, v99
	v_exp_f32_e32 v98, v98
	v_exp_f32_e32 v99, v99
	v_and_b32_e32 v107, 0xffff0000, v116
	v_lshlrev_b32_e32 v106, 16, v116
	v_add_f32_e32 v98, 1.0, v98
	v_add_f32_e32 v99, 1.0, v99
	v_rcp_f32_e32 v98, v98
	v_rcp_f32_e32 v99, v99
	v_add_f32_e32 v102, v102, v222
	v_add_f32_e32 v103, v103, v223
	v_mul_f32_e32 v102, 0xbfb8aa3b, v102
	v_pk_mul_f32 v[106:107], v[98:99], v[106:107]
	v_add_f32_e32 v99, v100, v228
	v_mul_f32_e32 v99, 0xbfb8aa3b, v99
	v_exp_f32_e32 v99, v99
	v_add_f32_e32 v98, v104, v224
	v_mul_f32_e32 v98, 0xbfb8aa3b, v98
	v_exp_f32_e32 v98, v98
	v_add_f32_e32 v99, 1.0, v99
	v_rcp_f32_e32 v100, v99
	v_add_f32_e32 v99, v105, v225
	v_mul_f32_e32 v99, 0xbfb8aa3b, v99
	v_exp_f32_e32 v99, v99
	v_add_f32_e32 v98, 1.0, v98
	v_rcp_f32_e32 v98, v98
	v_and_b32_e32 v105, 0xffff0000, v115
	v_add_f32_e32 v99, 1.0, v99
	v_rcp_f32_e32 v99, v99
	v_lshlrev_b32_e32 v104, 16, v115
	v_mul_f32_e32 v103, 0xbfb8aa3b, v103
	v_exp_f32_e32 v102, v102
	v_pk_mul_f32 v[104:105], v[98:99], v[104:105]
	v_add_f32_e32 v98, v101, v229
	v_mul_f32_e32 v98, 0xbfb8aa3b, v98
	v_exp_f32_e32 v103, v103
	v_exp_f32_e32 v98, v98
	v_add_f32_e32 v102, 1.0, v102
	v_rcp_f32_e32 v102, v102
	v_add_f32_e32 v103, 1.0, v103
	v_add_f32_e32 v98, 1.0, v98
	v_rcp_f32_e32 v103, v103
	v_rcp_f32_e32 v101, v98
	v_and_b32_e32 v99, 0xffff0000, v117
	v_lshlrev_b32_e32 v98, 16, v117
	v_pk_mul_f32 v[102:103], v[102:103], v[112:113]
	v_pk_mul_f32 v[108:109], v[100:101], v[98:99]
	v_cvt_pk_bf16_f32 v98, v102, v103
	v_cvt_pk_bf16_f32 v99, v104, v105
	v_cvt_pk_bf16_f32 v100, v106, v107
	v_cvt_pk_bf16_f32 v101, v108, v109
	global_store_dwordx4 v[110:111], v[98:101], off offset:256
	s_nop 1
	v_or_b32_e32 v98, 32, v180
	v_ashrrev_i32_e32 v99, 31, v98
	v_lshlrev_b64 v[120:121], 11, v[98:99]
	v_lshl_add_u64 v[98:99], s[24:25], 0, v[120:121]
	v_lshl_add_u64 v[98:99], v[98:99], 0, v[176:177]
	global_load_dwordx4 v[110:113], v[98:99], off
	global_load_dwordx4 v[106:109], v[98:99], off offset:256
	v_or_b32_e32 v98, 48, v180
	v_ashrrev_i32_e32 v99, 31, v98
	v_lshlrev_b64 v[118:119], 11, v[98:99]
	v_lshl_add_u64 v[98:99], s[24:25], 0, v[118:119]
	v_lshl_add_u64 v[98:99], v[98:99], 0, v[176:177]
	global_load_dwordx4 v[102:105], v[98:99], off
	s_nop 0
	global_load_dwordx4 v[98:101], v[98:99], off offset:256
	s_nop 0
	s_waitcnt vmcnt(0)
	v_add_f32_e32 v90, v90, v218
	v_add_f32_e32 v91, v91, v219
	v_mul_f32_e32 v90, 0xbfb8aa3b, v90
	v_mul_f32_e32 v91, 0xbfb8aa3b, v91
	v_exp_f32_e32 v90, v90
	v_exp_f32_e32 v91, v91
	v_and_b32_e32 v115, 0xffff0000, v112
	v_lshlrev_b32_e32 v114, 16, v112
	v_add_f32_e32 v90, 1.0, v90
	v_add_f32_e32 v91, 1.0, v91
	v_rcp_f32_e32 v90, v90
	v_rcp_f32_e32 v91, v91
	v_add_f32_e32 v94, v94, v214
	v_add_f32_e32 v95, v95, v215
	v_mul_f32_e32 v94, 0xbfb8aa3b, v94
	v_pk_mul_f32 v[114:115], v[90:91], v[114:115]
	v_add_f32_e32 v91, v92, v220
	v_mul_f32_e32 v91, 0xbfb8aa3b, v91
	v_exp_f32_e32 v91, v91
	v_add_f32_e32 v90, v96, v216
	v_mul_f32_e32 v90, 0xbfb8aa3b, v90
	v_exp_f32_e32 v90, v90
	v_add_f32_e32 v91, 1.0, v91
	v_rcp_f32_e32 v92, v91
	v_add_f32_e32 v91, v97, v217
	v_mul_f32_e32 v91, 0xbfb8aa3b, v91
	v_exp_f32_e32 v91, v91
	v_add_f32_e32 v90, 1.0, v90
	v_rcp_f32_e32 v90, v90
	v_and_b32_e32 v97, 0xffff0000, v111
	v_add_f32_e32 v91, 1.0, v91
	v_rcp_f32_e32 v91, v91
	v_lshlrev_b32_e32 v96, 16, v111
	v_mul_f32_e32 v95, 0xbfb8aa3b, v95
	v_exp_f32_e32 v94, v94
	v_pk_mul_f32 v[96:97], v[90:91], v[96:97]
	v_add_f32_e32 v90, v93, v221
	v_exp_f32_e32 v95, v95
	v_mul_f32_e32 v90, 0xbfb8aa3b, v90
	v_exp_f32_e32 v90, v90
	v_add_f32_e32 v94, 1.0, v94
	v_add_f32_e32 v95, 1.0, v95
	v_rcp_f32_e32 v94, v94
	v_rcp_f32_e32 v95, v95
	v_add_f32_e32 v90, 1.0, v90
	v_rcp_f32_e32 v93, v90
	v_and_b32_e32 v123, 0xffff0000, v110
	v_lshlrev_b32_e32 v122, 16, v110
	v_pk_mul_f32 v[94:95], v[94:95], v[122:123]
	v_and_b32_e32 v91, 0xffff0000, v113
	v_lshlrev_b32_e32 v90, 16, v113
	v_pk_mul_f32 v[110:111], v[92:93], v[90:91]
	v_cvt_pk_bf16_f32 v90, v94, v95
	v_lshl_add_u64 v[94:95], s[64:65], 0, v[120:121]
	v_cvt_pk_bf16_f32 v91, v96, v97
	v_cvt_pk_bf16_f32 v92, v114, v115
	v_cvt_pk_bf16_f32 v93, v110, v111
	v_lshl_add_u64 v[94:95], v[94:95], 0, v[176:177]
	global_store_dwordx4 v[94:95], v[90:93], off
	s_nop 0
	v_and_b32_e32 v97, 0xffff0000, v106
	v_lshlrev_b32_e32 v96, 16, v106
	v_add_f32_e32 v82, v82, v226
	v_add_f32_e32 v83, v83, v227
	v_mul_f32_e32 v82, 0xbfb8aa3b, v82
	v_mul_f32_e32 v83, 0xbfb8aa3b, v83
	v_add_f32_e32 v88, v88, v224
	v_add_f32_e32 v89, v89, v225
	v_add_f32_e32 v86, v86, v222
	v_exp_f32_e32 v82, v82
	v_add_f32_e32 v87, v87, v223
	v_exp_f32_e32 v83, v83
	v_mul_f32_e32 v88, 0xbfb8aa3b, v88
	v_add_f32_e32 v84, v84, v228
	v_mul_f32_e32 v89, 0xbfb8aa3b, v89
	v_add_f32_e32 v85, v85, v229
	v_mul_f32_e32 v86, 0xbfb8aa3b, v86
	v_mul_f32_e32 v87, 0xbfb8aa3b, v87
	v_exp_f32_e32 v88, v88
	v_mul_f32_e32 v84, 0xbfb8aa3b, v84
	v_exp_f32_e32 v89, v89
	v_mul_f32_e32 v85, 0xbfb8aa3b, v85
	v_exp_f32_e32 v86, v86
	v_exp_f32_e32 v87, v87
	v_exp_f32_e32 v84, v84
	v_exp_f32_e32 v85, v85
	v_add_f32_e32 v82, 1.0, v82
	v_add_f32_e32 v83, 1.0, v83
	v_rcp_f32_e32 v82, v82
	v_rcp_f32_e32 v83, v83
	v_add_f32_e32 v88, 1.0, v88
; template <class Epi>
; DEVI void gemm_phase(LAS unsigned char* lds, const Gemm g, const Epi& E) {
;     ...
; #pragma unroll
;                 for (int mm = 0; mm < 2; ++mm) {
;                     const int m = m0 + mm;
;                     const int r = row0 + ai * HALF + m * 16; float rs = 1.f, part = 0.f;
;                     if constexpr (Epi::RS) rs = rsv[ai * 4 + m];
;                     if constexpr (Epi::PAIR) E.pair8(cur.b, r, cur.pn * HALF + wc * 32 + 8 * fq, acc[ai][0][m][0] * rs, acc[ai][0][m][1] * rs, acc[ai][1][m][0] * rs, acc[ai][1][m][1] * rs);
;                     else
; #pragma unroll
;                     for (int bj = 0; bj < 2; ++bj) {
;                         const int c = col0 + bj * HALF; f32x4 v0 = acc[ai][bj][m][0], v1 = acc[ai][bj][m][1];
;                         if constexpr (Epi::RS) { v0 = v0 * rs; v1 = v1 * rs; }
;                         if constexpr (Epi::PRE) part += E.frag_pre8(cur.b, r, c, v0, v1, pre[mm][bj][0], pre[mm][bj][1]);
;                         else if constexpr (Epi::PERM) E.frag8(cur.b, r, c, v0, v1);
;                         else { E.frag(cur.b, r, c, v0); E.frag(cur.b, r, c + 16, v1); }
	v_add_f32_e32 v89, 1.0, v89
	v_add_f32_e32 v86, 1.0, v86
	v_add_f32_e32 v87, 1.0, v87
	v_rcp_f32_e32 v88, v88
	v_add_f32_e32 v84, 1.0, v84
	v_rcp_f32_e32 v89, v89
	v_add_f32_e32 v85, 1.0, v85
	v_rcp_f32_e32 v86, v86
	v_rcp_f32_e32 v87, v87
	v_rcp_f32_e32 v84, v84
	v_rcp_f32_e32 v85, v85
	v_and_b32_e32 v91, 0xffff0000, v108
	v_lshlrev_b32_e32 v90, 16, v108
	v_pk_mul_f32 v[82:83], v[82:83], v[90:91]
	v_and_b32_e32 v91, 0xffff0000, v107
	v_lshlrev_b32_e32 v90, 16, v107
	v_pk_mul_f32 v[88:89], v[88:89], v[90:91]
	v_and_b32_e32 v91, 0xffff0000, v109
	v_lshlrev_b32_e32 v90, 16, v109
	v_pk_mul_f32 v[86:87], v[86:87], v[96:97]
	v_pk_mul_f32 v[90:91], v[84:85], v[90:91]
	v_cvt_pk_bf16_f32 v84, v86, v87
	v_cvt_pk_bf16_f32 v85, v88, v89
	v_cvt_pk_bf16_f32 v86, v82, v83
	v_cvt_pk_bf16_f32 v87, v90, v91
	global_store_dwordx4 v[94:95], v[84:87], off offset:256
	s_nop 0
	v_add_f32_e32 v74, v74, v218
	v_add_f32_e32 v75, v75, v219
	v_mul_f32_e32 v74, 0xbfb8aa3b, v74
	v_mul_f32_e32 v75, 0xbfb8aa3b, v75
	v_exp_f32_e32 v74, v74
	v_exp_f32_e32 v75, v75
	v_and_b32_e32 v83, 0xffff0000, v104
	v_lshlrev_b32_e32 v82, 16, v104
	v_add_f32_e32 v74, 1.0, v74
	v_add_f32_e32 v75, 1.0, v75
	v_rcp_f32_e32 v74, v74
	v_rcp_f32_e32 v75, v75
	v_add_f32_e32 v78, v78, v214
	v_add_f32_e32 v79, v79, v215
	v_mul_f32_e32 v78, 0xbfb8aa3b, v78
	v_pk_mul_f32 v[82:83], v[74:75], v[82:83]
	v_add_f32_e32 v75, v76, v220
	v_mul_f32_e32 v75, 0xbfb8aa3b, v75
	v_exp_f32_e32 v75, v75
	v_add_f32_e32 v74, v80, v216
	v_mul_f32_e32 v74, 0xbfb8aa3b, v74
	v_exp_f32_e32 v74, v74
	v_add_f32_e32 v75, 1.0, v75
	v_rcp_f32_e32 v76, v75
	v_add_f32_e32 v75, v81, v217
	v_mul_f32_e32 v75, 0xbfb8aa3b, v75
	v_exp_f32_e32 v75, v75
	v_add_f32_e32 v74, 1.0, v74
	v_rcp_f32_e32 v74, v74
	v_and_b32_e32 v81, 0xffff0000, v103
	v_add_f32_e32 v75, 1.0, v75
	v_rcp_f32_e32 v75, v75
	v_lshlrev_b32_e32 v80, 16, v103
	v_mul_f32_e32 v79, 0xbfb8aa3b, v79
	v_exp_f32_e32 v78, v78
	v_pk_mul_f32 v[80:81], v[74:75], v[80:81]
	v_add_f32_e32 v74, v77, v221
	v_exp_f32_e32 v79, v79
	v_mul_f32_e32 v74, 0xbfb8aa3b, v74
	v_exp_f32_e32 v74, v74
	v_add_f32_e32 v78, 1.0, v78
	v_add_f32_e32 v79, 1.0, v79
	v_rcp_f32_e32 v78, v78
	v_rcp_f32_e32 v79, v79
	v_add_f32_e32 v74, 1.0, v74
	v_rcp_f32_e32 v77, v74
	v_and_b32_e32 v87, 0xffff0000, v102
	v_lshlrev_b32_e32 v86, 16, v102
	v_pk_mul_f32 v[78:79], v[78:79], v[86:87]
	v_and_b32_e32 v75, 0xffff0000, v105
	v_lshlrev_b32_e32 v74, 16, v105
	v_pk_mul_f32 v[84:85], v[76:77], v[74:75]
	v_cvt_pk_bf16_f32 v74, v78, v79
	v_lshl_add_u64 v[78:79], s[64:65], 0, v[118:119]
	v_cvt_pk_bf16_f32 v75, v80, v81
	v_cvt_pk_bf16_f32 v76, v82, v83
	v_cvt_pk_bf16_f32 v77, v84, v85
	v_lshl_add_u64 v[78:79], v[78:79], 0, v[176:177]
	global_store_dwordx4 v[78:79], v[74:77], off
	s_nop 0
	v_lshl_add_u64 v[88:89], v[178:179], 0, s[0:1]
	s_mov_b64 s[0:1], 0x48000
	v_lshl_add_u64 v[86:87], v[178:179], 0, s[0:1]
	s_mov_b64 s[0:1], 0x50000
	v_add_f32_e32 v66, v66, v226
	v_add_f32_e32 v67, v67, v227
	v_mul_f32_e32 v66, 0xbfb8aa3b, v66
	v_mul_f32_e32 v67, 0xbfb8aa3b, v67
	v_exp_f32_e32 v66, v66
	v_exp_f32_e32 v67, v67
	v_and_b32_e32 v75, 0xffff0000, v100
	v_lshlrev_b32_e32 v74, 16, v100
	v_add_f32_e32 v66, 1.0, v66
	v_add_f32_e32 v67, 1.0, v67
	v_rcp_f32_e32 v66, v66
	v_rcp_f32_e32 v67, v67
	v_add_f32_e32 v70, v70, v222
	v_add_f32_e32 v71, v71, v223
	v_mul_f32_e32 v70, 0xbfb8aa3b, v70
	v_pk_mul_f32 v[74:75], v[66:67], v[74:75]
	v_add_f32_e32 v67, v68, v228
	v_mul_f32_e32 v67, 0xbfb8aa3b, v67
	v_exp_f32_e32 v67, v67
	v_add_f32_e32 v66, v72, v224
	v_mul_f32_e32 v66, 0xbfb8aa3b, v66
	v_exp_f32_e32 v66, v66
	v_add_f32_e32 v67, 1.0, v67
	v_rcp_f32_e32 v68, v67
	v_add_f32_e32 v67, v73, v225
	v_mul_f32_e32 v67, 0xbfb8aa3b, v67
	v_exp_f32_e32 v67, v67
	v_add_f32_e32 v66, 1.0, v66
	v_rcp_f32_e32 v66, v66
	v_and_b32_e32 v73, 0xffff0000, v99
	v_add_f32_e32 v67, 1.0, v67
	v_rcp_f32_e32 v67, v67
	v_lshlrev_b32_e32 v72, 16, v99
	v_mul_f32_e32 v71, 0xbfb8aa3b, v71
	v_exp_f32_e32 v70, v70
	v_pk_mul_f32 v[72:73], v[66:67], v[72:73]
	v_add_f32_e32 v66, v69, v229
	v_mul_f32_e32 v66, 0xbfb8aa3b, v66
	v_exp_f32_e32 v71, v71
	v_exp_f32_e32 v66, v66
	v_add_f32_e32 v70, 1.0, v70
	v_rcp_f32_e32 v70, v70
	v_add_f32_e32 v71, 1.0, v71
	v_add_f32_e32 v66, 1.0, v66
	v_rcp_f32_e32 v71, v71
	v_rcp_f32_e32 v69, v66
	v_and_b32_e32 v81, 0xffff0000, v98
	v_lshlrev_b32_e32 v80, 16, v98
	v_and_b32_e32 v67, 0xffff0000, v101
	v_lshlrev_b32_e32 v66, 16, v101
	v_pk_mul_f32 v[70:71], v[70:71], v[80:81]
	v_pk_mul_f32 v[76:77], v[68:69], v[66:67]
	v_cvt_pk_bf16_f32 v66, v70, v71
	v_cvt_pk_bf16_f32 v67, v72, v73
	v_cvt_pk_bf16_f32 v68, v74, v75
	v_cvt_pk_bf16_f32 v69, v76, v77
	global_store_dwordx4 v[78:79], v[66:69], off offset:256
	s_nop 1
	v_lshl_add_u64 v[66:67], s[24:25], 0, v[88:89]
	v_lshl_add_u64 v[66:67], v[66:67], 0, v[176:177]
	global_load_dwordx4 v[78:81], v[66:67], off
	global_load_dwordx4 v[74:77], v[66:67], off offset:256
	v_lshl_add_u64 v[66:67], s[24:25], 0, v[86:87]
	v_lshl_add_u64 v[66:67], v[66:67], 0, v[176:177]
	global_load_dwordx4 v[70:73], v[66:67], off
	s_nop 0
	global_load_dwordx4 v[66:69], v[66:67], off offset:256
	s_nop 0
	s_waitcnt vmcnt(0)
; template <class Epi>
; DEVI void gemm_phase(LAS unsigned char* lds, const Gemm g, const Epi& E) {
;     ...
; #pragma unroll
;                 for (int mm = 0; mm < 2; ++mm) {
;                     const int m = m0 + mm;
;                     const int r = row0 + ai * HALF + m * 16; float rs = 1.f, part = 0.f;
;                     if constexpr (Epi::RS) rs = rsv[ai * 4 + m];
;                     if constexpr (Epi::PAIR) E.pair8(cur.b, r, cur.pn * HALF + wc * 32 + 8 * fq, acc[ai][0][m][0] * rs, acc[ai][0][m][1] * rs, acc[ai][1][m][0] * rs, acc[ai][1][m][1] * rs);
;                     else
; #pragma unroll
;                     for (int bj = 0; bj < 2; ++bj) {
;                         const int c = col0 + bj * HALF; f32x4 v0 = acc[ai][bj][m][0], v1 = acc[ai][bj][m][1];
;                         if constexpr (Epi::RS) { v0 = v0 * rs; v1 = v1 * rs; }
;                         if constexpr (Epi::PRE) part += E.frag_pre8(cur.b, r, c, v0, v1, pre[mm][bj][0], pre[mm][bj][1]);
;                         else if constexpr (Epi::PERM) E.frag8(cur.b, r, c, v0, v1);
;                         else { E.frag(cur.b, r, c, v0); E.frag(cur.b, r, c + 16, v1); }
	v_add_f32_e32 v58, v58, v218
	v_add_f32_e32 v59, v59, v219
	v_mul_f32_e32 v58, 0xbfb8aa3b, v58
	v_mul_f32_e32 v59, 0xbfb8aa3b, v59
	v_exp_f32_e32 v58, v58
	v_exp_f32_e32 v59, v59
	v_and_b32_e32 v83, 0xffff0000, v80
	v_lshlrev_b32_e32 v82, 16, v80
	v_add_f32_e32 v58, 1.0, v58
	v_add_f32_e32 v59, 1.0, v59
	v_rcp_f32_e32 v58, v58
	v_rcp_f32_e32 v59, v59
	v_add_f32_e32 v62, v62, v214
	v_add_f32_e32 v63, v63, v215
	v_mul_f32_e32 v62, 0xbfb8aa3b, v62
	v_pk_mul_f32 v[82:83], v[58:59], v[82:83]
	v_add_f32_e32 v59, v60, v220
	v_mul_f32_e32 v59, 0xbfb8aa3b, v59
	v_exp_f32_e32 v59, v59
	v_add_f32_e32 v58, v64, v216
	v_mul_f32_e32 v58, 0xbfb8aa3b, v58
	v_exp_f32_e32 v58, v58
	v_add_f32_e32 v59, 1.0, v59
	v_rcp_f32_e32 v60, v59
	v_add_f32_e32 v59, v65, v217
	v_mul_f32_e32 v59, 0xbfb8aa3b, v59
	v_exp_f32_e32 v59, v59
	v_add_f32_e32 v58, 1.0, v58
	v_rcp_f32_e32 v58, v58
	v_and_b32_e32 v65, 0xffff0000, v79
	v_add_f32_e32 v59, 1.0, v59
	v_rcp_f32_e32 v59, v59
	v_lshlrev_b32_e32 v64, 16, v79
	v_mul_f32_e32 v63, 0xbfb8aa3b, v63
	v_exp_f32_e32 v62, v62
	v_pk_mul_f32 v[64:65], v[58:59], v[64:65]
	v_add_f32_e32 v58, v61, v221
	v_exp_f32_e32 v63, v63
	v_mul_f32_e32 v58, 0xbfb8aa3b, v58
	v_exp_f32_e32 v58, v58
	v_add_f32_e32 v62, 1.0, v62
	v_add_f32_e32 v63, 1.0, v63
	v_rcp_f32_e32 v62, v62
	v_rcp_f32_e32 v63, v63
	v_add_f32_e32 v58, 1.0, v58
	v_rcp_f32_e32 v61, v58
	v_and_b32_e32 v91, 0xffff0000, v78
	v_lshlrev_b32_e32 v90, 16, v78
	v_pk_mul_f32 v[62:63], v[62:63], v[90:91]
	v_and_b32_e32 v59, 0xffff0000, v81
	v_lshlrev_b32_e32 v58, 16, v81
	v_pk_mul_f32 v[78:79], v[60:61], v[58:59]
	v_cvt_pk_bf16_f32 v58, v62, v63
	v_lshl_add_u64 v[62:63], s[64:65], 0, v[88:89]
	v_cvt_pk_bf16_f32 v59, v64, v65
	v_cvt_pk_bf16_f32 v60, v82, v83
	v_cvt_pk_bf16_f32 v61, v78, v79
	v_lshl_add_u64 v[62:63], v[62:63], 0, v[176:177]
	global_store_dwordx4 v[62:63], v[58:61], off
	s_nop 0
	v_and_b32_e32 v65, 0xffff0000, v74
	v_lshlrev_b32_e32 v64, 16, v74
	v_add_f32_e32 v50, v50, v226
	v_add_f32_e32 v51, v51, v227
	v_mul_f32_e32 v50, 0xbfb8aa3b, v50
	v_mul_f32_e32 v51, 0xbfb8aa3b, v51
	v_add_f32_e32 v56, v56, v224
	v_add_f32_e32 v57, v57, v225
	v_add_f32_e32 v54, v54, v222
	v_exp_f32_e32 v50, v50
	v_add_f32_e32 v55, v55, v223
	v_exp_f32_e32 v51, v51
	v_mul_f32_e32 v56, 0xbfb8aa3b, v56
	v_add_f32_e32 v52, v52, v228
	v_mul_f32_e32 v57, 0xbfb8aa3b, v57
	v_add_f32_e32 v53, v53, v229
	v_mul_f32_e32 v54, 0xbfb8aa3b, v54
	v_mul_f32_e32 v55, 0xbfb8aa3b, v55
	v_exp_f32_e32 v56, v56
	v_mul_f32_e32 v52, 0xbfb8aa3b, v52
	v_exp_f32_e32 v57, v57
	v_mul_f32_e32 v53, 0xbfb8aa3b, v53
	v_exp_f32_e32 v54, v54
	v_exp_f32_e32 v55, v55
	v_exp_f32_e32 v52, v52
	v_exp_f32_e32 v53, v53
	v_add_f32_e32 v50, 1.0, v50
	v_add_f32_e32 v51, 1.0, v51
	v_rcp_f32_e32 v50, v50
	v_rcp_f32_e32 v51, v51
	v_add_f32_e32 v56, 1.0, v56
	v_add_f32_e32 v57, 1.0, v57
	v_add_f32_e32 v54, 1.0, v54
	v_add_f32_e32 v55, 1.0, v55
	v_rcp_f32_e32 v56, v56
	v_add_f32_e32 v52, 1.0, v52
	v_rcp_f32_e32 v57, v57
	v_add_f32_e32 v53, 1.0, v53
	v_rcp_f32_e32 v54, v54
	v_rcp_f32_e32 v55, v55
	v_rcp_f32_e32 v52, v52
	v_rcp_f32_e32 v53, v53
	v_and_b32_e32 v59, 0xffff0000, v76
	v_lshlrev_b32_e32 v58, 16, v76
	v_pk_mul_f32 v[50:51], v[50:51], v[58:59]
	v_and_b32_e32 v59, 0xffff0000, v75
	v_lshlrev_b32_e32 v58, 16, v75
	v_pk_mul_f32 v[56:57], v[56:57], v[58:59]
	v_and_b32_e32 v59, 0xffff0000, v77
	v_lshlrev_b32_e32 v58, 16, v77
	v_pk_mul_f32 v[54:55], v[54:55], v[64:65]
	v_pk_mul_f32 v[58:59], v[52:53], v[58:59]
	v_cvt_pk_bf16_f32 v52, v54, v55
	v_cvt_pk_bf16_f32 v53, v56, v57
	v_cvt_pk_bf16_f32 v54, v50, v51
	v_cvt_pk_bf16_f32 v55, v58, v59
	global_store_dwordx4 v[62:63], v[52:55], off offset:256
	s_nop 0
	v_add_f32_e32 v42, v42, v218
	v_add_f32_e32 v43, v43, v219
	v_mul_f32_e32 v42, 0xbfb8aa3b, v42
	v_mul_f32_e32 v43, 0xbfb8aa3b, v43
	v_exp_f32_e32 v42, v42
	v_exp_f32_e32 v43, v43
	v_and_b32_e32 v51, 0xffff0000, v72
	v_lshlrev_b32_e32 v50, 16, v72
	v_add_f32_e32 v42, 1.0, v42
	v_add_f32_e32 v43, 1.0, v43
	v_rcp_f32_e32 v42, v42
	v_rcp_f32_e32 v43, v43
	v_add_f32_e32 v46, v46, v214
	v_add_f32_e32 v47, v47, v215
	v_mul_f32_e32 v46, 0xbfb8aa3b, v46
	v_pk_mul_f32 v[50:51], v[42:43], v[50:51]
	v_add_f32_e32 v43, v44, v220
	v_mul_f32_e32 v43, 0xbfb8aa3b, v43
	v_exp_f32_e32 v43, v43
	v_add_f32_e32 v42, v48, v216
	v_mul_f32_e32 v42, 0xbfb8aa3b, v42
	v_exp_f32_e32 v42, v42
	v_add_f32_e32 v43, 1.0, v43
	v_rcp_f32_e32 v44, v43
	v_add_f32_e32 v43, v49, v217
	v_mul_f32_e32 v43, 0xbfb8aa3b, v43
	v_exp_f32_e32 v43, v43
	v_add_f32_e32 v42, 1.0, v42
	v_rcp_f32_e32 v42, v42
	v_and_b32_e32 v49, 0xffff0000, v71
	v_add_f32_e32 v43, 1.0, v43
	v_rcp_f32_e32 v43, v43
	v_lshlrev_b32_e32 v48, 16, v71
	v_mul_f32_e32 v47, 0xbfb8aa3b, v47
	v_exp_f32_e32 v46, v46
	v_pk_mul_f32 v[48:49], v[42:43], v[48:49]
	v_add_f32_e32 v42, v45, v221
	v_exp_f32_e32 v47, v47
	v_mul_f32_e32 v42, 0xbfb8aa3b, v42
	v_exp_f32_e32 v42, v42
	v_add_f32_e32 v46, 1.0, v46
	v_add_f32_e32 v47, 1.0, v47
	v_rcp_f32_e32 v46, v46
	v_rcp_f32_e32 v47, v47
	v_add_f32_e32 v42, 1.0, v42
	v_rcp_f32_e32 v45, v42
	v_and_b32_e32 v55, 0xffff0000, v70
	v_lshlrev_b32_e32 v54, 16, v70
	v_pk_mul_f32 v[46:47], v[46:47], v[54:55]
	v_and_b32_e32 v43, 0xffff0000, v73
	v_lshlrev_b32_e32 v42, 16, v73
	v_pk_mul_f32 v[52:53], v[44:45], v[42:43]
	v_cvt_pk_bf16_f32 v42, v46, v47
	v_lshl_add_u64 v[46:47], s[64:65], 0, v[86:87]
	v_cvt_pk_bf16_f32 v43, v48, v49
	v_cvt_pk_bf16_f32 v44, v50, v51
	v_cvt_pk_bf16_f32 v45, v52, v53
	v_lshl_add_u64 v[46:47], v[46:47], 0, v[176:177]
	global_store_dwordx4 v[46:47], v[42:45], off
	s_nop 0
	v_lshl_add_u64 v[56:57], v[178:179], 0, s[0:1]
	s_mov_b64 s[0:1], 0x58000
	v_lshl_add_u64 v[54:55], v[178:179], 0, s[0:1]
; template <class Epi>
; DEVI void gemm_phase(LAS unsigned char* lds, const Gemm g, const Epi& E) {
;     ...
; #pragma unroll
;                 for (int mm = 0; mm < 2; ++mm) {
;                     const int m = m0 + mm;
;                     const int r = row0 + ai * HALF + m * 16; float rs = 1.f, part = 0.f;
;                     if constexpr (Epi::RS) rs = rsv[ai * 4 + m];
;                     if constexpr (Epi::PAIR) E.pair8(cur.b, r, cur.pn * HALF + wc * 32 + 8 * fq, acc[ai][0][m][0] * rs, acc[ai][0][m][1] * rs, acc[ai][1][m][0] * rs, acc[ai][1][m][1] * rs);
;                     else
; #pragma unroll
;                     for (int bj = 0; bj < 2; ++bj) {
;                         const int c = col0 + bj * HALF; f32x4 v0 = acc[ai][bj][m][0], v1 = acc[ai][bj][m][1];
;                         if constexpr (Epi::RS) { v0 = v0 * rs; v1 = v1 * rs; }
;                         if constexpr (Epi::PRE) part += E.frag_pre8(cur.b, r, c, v0, v1, pre[mm][bj][0], pre[mm][bj][1]);
;                         else if constexpr (Epi::PERM) E.frag8(cur.b, r, c, v0, v1);
;                         else { E.frag(cur.b, r, c, v0); E.frag(cur.b, r, c + 16, v1); }
	s_mov_b32 s0, s4
	v_add_f32_e32 v34, v34, v226
	v_add_f32_e32 v35, v35, v227
	v_mul_f32_e32 v34, 0xbfb8aa3b, v34
	v_mul_f32_e32 v35, 0xbfb8aa3b, v35
	v_exp_f32_e32 v34, v34
	v_exp_f32_e32 v35, v35
	v_and_b32_e32 v43, 0xffff0000, v68
	v_lshlrev_b32_e32 v42, 16, v68
	v_add_f32_e32 v34, 1.0, v34
	v_add_f32_e32 v35, 1.0, v35
	v_rcp_f32_e32 v34, v34
	v_rcp_f32_e32 v35, v35
	v_add_f32_e32 v38, v38, v222
	v_add_f32_e32 v39, v39, v223
	v_mul_f32_e32 v38, 0xbfb8aa3b, v38
	v_pk_mul_f32 v[42:43], v[34:35], v[42:43]
	v_add_f32_e32 v35, v36, v228
	v_mul_f32_e32 v35, 0xbfb8aa3b, v35
	v_exp_f32_e32 v35, v35
	v_add_f32_e32 v34, v40, v224
	v_mul_f32_e32 v34, 0xbfb8aa3b, v34
	v_exp_f32_e32 v34, v34
	v_add_f32_e32 v35, 1.0, v35
	v_rcp_f32_e32 v36, v35
	v_add_f32_e32 v35, v41, v225
	v_mul_f32_e32 v35, 0xbfb8aa3b, v35
	v_exp_f32_e32 v35, v35
	v_add_f32_e32 v34, 1.0, v34
	v_rcp_f32_e32 v34, v34
	v_and_b32_e32 v41, 0xffff0000, v67
	v_add_f32_e32 v35, 1.0, v35
	v_rcp_f32_e32 v35, v35
	v_lshlrev_b32_e32 v40, 16, v67
	v_mul_f32_e32 v39, 0xbfb8aa3b, v39
	v_exp_f32_e32 v38, v38
	v_pk_mul_f32 v[40:41], v[34:35], v[40:41]
	v_add_f32_e32 v34, v37, v229
	v_mul_f32_e32 v34, 0xbfb8aa3b, v34
	v_exp_f32_e32 v39, v39
	v_exp_f32_e32 v34, v34
	v_add_f32_e32 v38, 1.0, v38
	v_rcp_f32_e32 v38, v38
	v_add_f32_e32 v39, 1.0, v39
	v_add_f32_e32 v34, 1.0, v34
	v_rcp_f32_e32 v39, v39
	v_rcp_f32_e32 v37, v34
	v_and_b32_e32 v49, 0xffff0000, v66
	v_lshlrev_b32_e32 v48, 16, v66
	v_and_b32_e32 v35, 0xffff0000, v69
	v_lshlrev_b32_e32 v34, 16, v69
	v_pk_mul_f32 v[38:39], v[38:39], v[48:49]
	v_pk_mul_f32 v[44:45], v[36:37], v[34:35]
	v_cvt_pk_bf16_f32 v34, v38, v39
	v_cvt_pk_bf16_f32 v35, v40, v41
	v_cvt_pk_bf16_f32 v36, v42, v43
	v_cvt_pk_bf16_f32 v37, v44, v45
	global_store_dwordx4 v[46:47], v[34:37], off offset:256
	s_nop 1
	v_lshl_add_u64 v[34:35], s[24:25], 0, v[56:57]
	v_lshl_add_u64 v[34:35], v[34:35], 0, v[176:177]
	global_load_dwordx4 v[46:49], v[34:35], off
	global_load_dwordx4 v[42:45], v[34:35], off offset:256
	v_lshl_add_u64 v[34:35], s[24:25], 0, v[54:55]
	v_lshl_add_u64 v[34:35], v[34:35], 0, v[176:177]
	global_load_dwordx4 v[38:41], v[34:35], off
	s_nop 0
	global_load_dwordx4 v[34:37], v[34:35], off offset:256
	s_nop 0
	s_waitcnt vmcnt(0)
	v_add_f32_e32 v26, v26, v218
	v_add_f32_e32 v27, v27, v219
	v_mul_f32_e32 v26, 0xbfb8aa3b, v26
	v_mul_f32_e32 v27, 0xbfb8aa3b, v27
	v_exp_f32_e32 v26, v26
	v_exp_f32_e32 v27, v27
	v_and_b32_e32 v51, 0xffff0000, v48
	v_lshlrev_b32_e32 v50, 16, v48
	v_add_f32_e32 v26, 1.0, v26
	v_add_f32_e32 v27, 1.0, v27
	v_rcp_f32_e32 v26, v26
	v_rcp_f32_e32 v27, v27
	v_add_f32_e32 v30, v30, v214
	v_add_f32_e32 v31, v31, v215
	v_mul_f32_e32 v30, 0xbfb8aa3b, v30
	v_pk_mul_f32 v[50:51], v[26:27], v[50:51]
	v_add_f32_e32 v27, v28, v220
	v_mul_f32_e32 v27, 0xbfb8aa3b, v27
	v_exp_f32_e32 v27, v27
	v_add_f32_e32 v26, v32, v216
	v_mul_f32_e32 v26, 0xbfb8aa3b, v26
	v_exp_f32_e32 v26, v26
	v_add_f32_e32 v27, 1.0, v27
	v_rcp_f32_e32 v28, v27
	v_add_f32_e32 v27, v33, v217
	v_mul_f32_e32 v27, 0xbfb8aa3b, v27
	v_exp_f32_e32 v27, v27
	v_add_f32_e32 v26, 1.0, v26
	v_rcp_f32_e32 v26, v26
	v_and_b32_e32 v33, 0xffff0000, v47
	v_add_f32_e32 v27, 1.0, v27
	v_rcp_f32_e32 v27, v27
	v_lshlrev_b32_e32 v32, 16, v47
	v_mul_f32_e32 v31, 0xbfb8aa3b, v31
	v_exp_f32_e32 v30, v30
	v_pk_mul_f32 v[32:33], v[26:27], v[32:33]
	v_add_f32_e32 v26, v29, v221
	v_exp_f32_e32 v31, v31
	v_mul_f32_e32 v26, 0xbfb8aa3b, v26
	v_exp_f32_e32 v26, v26
	v_add_f32_e32 v30, 1.0, v30
	v_add_f32_e32 v31, 1.0, v31
	v_rcp_f32_e32 v30, v30
	v_rcp_f32_e32 v31, v31
	v_add_f32_e32 v26, 1.0, v26
	v_rcp_f32_e32 v29, v26
	v_and_b32_e32 v59, 0xffff0000, v46
	v_lshlrev_b32_e32 v58, 16, v46
	v_pk_mul_f32 v[30:31], v[30:31], v[58:59]
	v_and_b32_e32 v27, 0xffff0000, v49
	v_lshlrev_b32_e32 v26, 16, v49
	v_pk_mul_f32 v[46:47], v[28:29], v[26:27]
	v_cvt_pk_bf16_f32 v26, v30, v31
	v_lshl_add_u64 v[30:31], s[64:65], 0, v[56:57]
	v_cvt_pk_bf16_f32 v27, v32, v33
	v_cvt_pk_bf16_f32 v28, v50, v51
	v_cvt_pk_bf16_f32 v29, v46, v47
	v_lshl_add_u64 v[30:31], v[30:31], 0, v[176:177]
	global_store_dwordx4 v[30:31], v[26:29], off
	s_nop 0
	v_and_b32_e32 v33, 0xffff0000, v42
	v_lshlrev_b32_e32 v32, 16, v42
	v_add_f32_e32 v18, v18, v226
	v_add_f32_e32 v19, v19, v227
	v_mul_f32_e32 v18, 0xbfb8aa3b, v18
	v_mul_f32_e32 v19, 0xbfb8aa3b, v19
	v_add_f32_e32 v24, v24, v224
	v_add_f32_e32 v25, v25, v225
	v_add_f32_e32 v22, v22, v222
	v_exp_f32_e32 v18, v18
	v_add_f32_e32 v23, v23, v223
	v_exp_f32_e32 v19, v19
	v_mul_f32_e32 v24, 0xbfb8aa3b, v24
	v_add_f32_e32 v20, v20, v228
	v_mul_f32_e32 v25, 0xbfb8aa3b, v25
	v_add_f32_e32 v21, v21, v229
	v_mul_f32_e32 v22, 0xbfb8aa3b, v22
	v_mul_f32_e32 v23, 0xbfb8aa3b, v23
	v_exp_f32_e32 v24, v24
	v_mul_f32_e32 v20, 0xbfb8aa3b, v20
	v_exp_f32_e32 v25, v25
; template <class Epi>
; DEVI void gemm_phase(LAS unsigned char* lds, const Gemm g, const Epi& E) {
;     ...
; #pragma unroll
;                 for (int mm = 0; mm < 2; ++mm) {
;                     const int m = m0 + mm;
;                     const int r = row0 + ai * HALF + m * 16; float rs = 1.f, part = 0.f;
;                     if constexpr (Epi::RS) rs = rsv[ai * 4 + m];
;                     if constexpr (Epi::PAIR) E.pair8(cur.b, r, cur.pn * HALF + wc * 32 + 8 * fq, acc[ai][0][m][0] * rs, acc[ai][0][m][1] * rs, acc[ai][1][m][0] * rs, acc[ai][1][m][1] * rs);
;                     else
; #pragma unroll
;                     for (int bj = 0; bj < 2; ++bj) {
;                         const int c = col0 + bj * HALF; f32x4 v0 = acc[ai][bj][m][0], v1 = acc[ai][bj][m][1];
;                         if constexpr (Epi::RS) { v0 = v0 * rs; v1 = v1 * rs; }
;                         if constexpr (Epi::PRE) part += E.frag_pre8(cur.b, r, c, v0, v1, pre[mm][bj][0], pre[mm][bj][1]);
;                         else if constexpr (Epi::PERM) E.frag8(cur.b, r, c, v0, v1);
;                         else { E.frag(cur.b, r, c, v0); E.frag(cur.b, r, c + 16, v1); }
	v_mul_f32_e32 v21, 0xbfb8aa3b, v21
	v_exp_f32_e32 v22, v22
	v_exp_f32_e32 v23, v23
	v_exp_f32_e32 v20, v20
	v_exp_f32_e32 v21, v21
	v_add_f32_e32 v18, 1.0, v18
	v_add_f32_e32 v19, 1.0, v19
	v_rcp_f32_e32 v18, v18
	v_rcp_f32_e32 v19, v19
	v_add_f32_e32 v24, 1.0, v24
	v_add_f32_e32 v25, 1.0, v25
	v_add_f32_e32 v22, 1.0, v22
	v_add_f32_e32 v23, 1.0, v23
	v_rcp_f32_e32 v24, v24
	v_add_f32_e32 v20, 1.0, v20
	v_rcp_f32_e32 v25, v25
	v_add_f32_e32 v21, 1.0, v21
	v_rcp_f32_e32 v22, v22
	v_rcp_f32_e32 v23, v23
	v_rcp_f32_e32 v20, v20
	v_rcp_f32_e32 v21, v21
	v_and_b32_e32 v27, 0xffff0000, v44
	v_lshlrev_b32_e32 v26, 16, v44
	v_pk_mul_f32 v[18:19], v[18:19], v[26:27]
	v_and_b32_e32 v27, 0xffff0000, v43
	v_lshlrev_b32_e32 v26, 16, v43
	v_pk_mul_f32 v[24:25], v[24:25], v[26:27]
	v_and_b32_e32 v27, 0xffff0000, v45
	v_lshlrev_b32_e32 v26, 16, v45
	v_pk_mul_f32 v[22:23], v[22:23], v[32:33]
	v_pk_mul_f32 v[26:27], v[20:21], v[26:27]
	v_cvt_pk_bf16_f32 v20, v22, v23
	v_cvt_pk_bf16_f32 v21, v24, v25
	v_cvt_pk_bf16_f32 v22, v18, v19
	v_cvt_pk_bf16_f32 v23, v26, v27
	global_store_dwordx4 v[30:31], v[20:23], off offset:256
	s_nop 0
	v_add_f32_e32 v10, v10, v218
	v_add_f32_e32 v11, v11, v219
	v_mul_f32_e32 v10, 0xbfb8aa3b, v10
	v_mul_f32_e32 v11, 0xbfb8aa3b, v11
	v_exp_f32_e32 v10, v10
	v_exp_f32_e32 v11, v11
	v_and_b32_e32 v19, 0xffff0000, v40
	v_lshlrev_b32_e32 v18, 16, v40
	v_add_f32_e32 v10, 1.0, v10
	v_add_f32_e32 v11, 1.0, v11
	v_rcp_f32_e32 v10, v10
	v_rcp_f32_e32 v11, v11
	v_add_f32_e32 v14, v14, v214
	v_add_f32_e32 v15, v15, v215
	v_mul_f32_e32 v14, 0xbfb8aa3b, v14
	v_pk_mul_f32 v[18:19], v[10:11], v[18:19]
	v_add_f32_e32 v11, v12, v220
	v_mul_f32_e32 v11, 0xbfb8aa3b, v11
	v_exp_f32_e32 v11, v11
	v_add_f32_e32 v10, v16, v216
	v_mul_f32_e32 v10, 0xbfb8aa3b, v10
	v_exp_f32_e32 v10, v10
	v_add_f32_e32 v11, 1.0, v11
	v_rcp_f32_e32 v12, v11
	v_add_f32_e32 v11, v17, v217
	v_mul_f32_e32 v11, 0xbfb8aa3b, v11
	v_exp_f32_e32 v11, v11
	v_add_f32_e32 v10, 1.0, v10
	v_rcp_f32_e32 v10, v10
	v_and_b32_e32 v17, 0xffff0000, v39
	v_add_f32_e32 v11, 1.0, v11
	v_rcp_f32_e32 v11, v11
	v_lshlrev_b32_e32 v16, 16, v39
	v_mul_f32_e32 v15, 0xbfb8aa3b, v15
	v_exp_f32_e32 v14, v14
	v_pk_mul_f32 v[16:17], v[10:11], v[16:17]
	v_add_f32_e32 v10, v13, v221
	v_exp_f32_e32 v15, v15
	v_mul_f32_e32 v10, 0xbfb8aa3b, v10
	v_exp_f32_e32 v10, v10
	v_add_f32_e32 v14, 1.0, v14
	v_add_f32_e32 v15, 1.0, v15
	v_rcp_f32_e32 v14, v14
	v_rcp_f32_e32 v15, v15
	v_add_f32_e32 v10, 1.0, v10
	v_rcp_f32_e32 v13, v10
	v_and_b32_e32 v23, 0xffff0000, v38
	v_lshlrev_b32_e32 v22, 16, v38
	v_pk_mul_f32 v[14:15], v[14:15], v[22:23]
	v_and_b32_e32 v11, 0xffff0000, v41
	v_lshlrev_b32_e32 v10, 16, v41
	v_pk_mul_f32 v[20:21], v[12:13], v[10:11]
	v_cvt_pk_bf16_f32 v10, v14, v15
	v_lshl_add_u64 v[14:15], s[64:65], 0, v[54:55]
	v_cvt_pk_bf16_f32 v11, v16, v17
	v_cvt_pk_bf16_f32 v12, v18, v19
	v_cvt_pk_bf16_f32 v13, v20, v21
	v_lshl_add_u64 v[14:15], v[14:15], 0, v[176:177]
	global_store_dwordx4 v[14:15], v[10:13], off
	s_nop 0
	v_add_f32_e32 v0, v0, v226
	v_add_f32_e32 v1, v1, v227
	v_mul_f32_e32 v0, 0xbfb8aa3b, v0
	v_mul_f32_e32 v1, 0xbfb8aa3b, v1
	v_exp_f32_e32 v0, v0
	v_exp_f32_e32 v1, v1
	v_and_b32_e32 v11, 0xffff0000, v36
	v_lshlrev_b32_e32 v10, 16, v36
	v_add_f32_e32 v0, 1.0, v0
	v_add_f32_e32 v1, 1.0, v1
	v_rcp_f32_e32 v0, v0
	v_rcp_f32_e32 v1, v1
	v_add_f32_e32 v4, v4, v222
	v_add_f32_e32 v5, v5, v223
	v_mul_f32_e32 v4, 0xbfb8aa3b, v4
	v_pk_mul_f32 v[10:11], v[0:1], v[10:11]
	v_add_f32_e32 v1, v2, v228
	v_mul_f32_e32 v1, 0xbfb8aa3b, v1
	v_exp_f32_e32 v1, v1
	v_add_f32_e32 v0, v6, v224
	v_mul_f32_e32 v0, 0xbfb8aa3b, v0
	v_exp_f32_e32 v0, v0
	v_add_f32_e32 v1, 1.0, v1
	v_rcp_f32_e32 v2, v1
	v_add_f32_e32 v1, v7, v225
	v_mul_f32_e32 v1, 0xbfb8aa3b, v1
	v_exp_f32_e32 v1, v1
	v_add_f32_e32 v0, 1.0, v0
	v_rcp_f32_e32 v0, v0
	v_and_b32_e32 v7, 0xffff0000, v35
	v_add_f32_e32 v1, 1.0, v1
	v_rcp_f32_e32 v1, v1
	v_lshlrev_b32_e32 v6, 16, v35
	v_mul_f32_e32 v5, 0xbfb8aa3b, v5
	v_exp_f32_e32 v4, v4
	v_pk_mul_f32 v[6:7], v[0:1], v[6:7]
	v_add_f32_e32 v0, v3, v229
	v_mul_f32_e32 v0, 0xbfb8aa3b, v0
	v_exp_f32_e32 v5, v5
	v_exp_f32_e32 v0, v0
	v_add_f32_e32 v4, 1.0, v4
	v_rcp_f32_e32 v4, v4
	v_add_f32_e32 v5, 1.0, v5
	v_add_f32_e32 v0, 1.0, v0
	v_rcp_f32_e32 v5, v5
	v_rcp_f32_e32 v3, v0
	v_and_b32_e32 v17, 0xffff0000, v34
	v_lshlrev_b32_e32 v16, 16, v34
	v_and_b32_e32 v1, 0xffff0000, v37
	v_lshlrev_b32_e32 v0, 16, v37
	v_pk_mul_f32 v[4:5], v[4:5], v[16:17]
	v_pk_mul_f32 v[12:13], v[2:3], v[0:1]
	v_cvt_pk_bf16_f32 v0, v4, v5
	v_cvt_pk_bf16_f32 v1, v6, v7
	v_cvt_pk_bf16_f32 v2, v10, v11
	v_cvt_pk_bf16_f32 v3, v12, v13
	global_store_dwordx4 v[14:15], v[0:3], off offset:256
	s_cbranch_vccz .LBB0_1339
	s_waitcnt vmcnt(0)
	s_cmpk_gt_u32 s46, 0xff
	s_cbranch_scc1 .LBB0_1350
	s_barrier
